# NA V-tile LDS writes as ds_write_b64 with immediate offsets
# baseline (speedup 1.0000x reference)
.LBB0_713:
	v_mov_b32_e32 v105, v179
	s_and_b64 vcc, exec, s[74:75]
	v_lshlrev_b32_e32 v104, 4, v105
	v_and_b32_e32 v104, 0x70, v104
	v_add_u32_e32 v104, s40, v104
	v_add_u32_e32 v104, 0x2848, v104
	s_cbranch_vccnz .LBB0_720
	v_ashrrev_i32_e32 v107, 3, v105
	v_mul_u32_u24_e32 v107, 0x88, v107
	v_add_u32_e32 v236, v104, v107
	s_waitcnt vmcnt(0)
	ds_write_b64 v236, v[60:61]
	ds_write_b64 v236, v[62:63] offset:8
	ds_write_b64 v236, v[56:57] offset:1088
	ds_write_b64 v236, v[58:59] offset:1096
	ds_write_b64 v236, v[48:49] offset:2176
	ds_write_b64 v236, v[50:51] offset:2184
	ds_write_b64 v236, v[40:41] offset:3264
	ds_write_b64 v236, v[42:43] offset:3272
	s_and_b64 vcc, exec, s[76:77]
	s_cbranch_vccz .LBB0_721

.LBB0_721:
	v_ashrrev_i32_e32 v107, 3, v105
	v_mul_u32_u24_e32 v107, 0x88, v107
	v_add_u32_e32 v236, v104, v107
	s_waitcnt vmcnt(0)
	ds_write_b64 v236, v[36:37] offset:4352
	ds_write_b64 v236, v[38:39] offset:4360
	ds_write_b64 v236, v[28:29] offset:5440
	ds_write_b64 v236, v[30:31] offset:5448
	ds_write_b64 v236, v[20:21] offset:6528
	ds_write_b64 v236, v[22:23] offset:6536
	ds_write_b64 v236, v[12:13] offset:7616
	ds_write_b64 v236, v[14:15] offset:7624
	s_and_b64 vcc, exec, s[22:23]
	s_cbranch_vccnz .LBB0_716
